# baseline (speedup 1.0000x reference)
; __global__ void __launch_bounds__(NTHREADS) fwd_megakernel(Params p) {
;     ...
;     if (tid == 0) pend = (int)atomicAdd(&ctr[rep_ * 24 + xq], 1u);
;     for (;;) {
;       __syncthreads();
;       if (tid == 0) s_item = pend;
;       __syncthreads();
;       const int n = s_item;
;       if (n >= 192) break;
;       if (tid == 0) pend = (int)atomicAdd(&ctr[rep_ * 24 + xq], 1u);
.LBB0_1125:
	s_barrier
	s_waitcnt vmcnt(63)
	s_and_saveexec_b64 s[2:3], s[0:1]
	ds_write_b32 v181, v193
	s_or_b64 exec, exec, s[2:3]
	s_waitcnt lgkmcnt(0)
	s_barrier
	ds_read_b32 v0, v181
	s_movk_i32 s2, 0xbf
	s_waitcnt lgkmcnt(0)
	v_cmp_lt_i32_e64 s[2:3], s2, v0
	v_readfirstlane_b32 s56, v0
	s_and_b64 vcc, exec, s[2:3]
	s_cbranch_vccnz .LBB0_1124
	s_and_saveexec_b64 s[4:5], s[0:1]
	s_cbranch_execz .LBB0_1132
	s_mov_b64 s[52:53], exec
	v_mbcnt_lo_u32_b32 v0, s52, 0
	v_mbcnt_hi_u32_b32 v0, s53, v0
	v_cmp_eq_u32_e32 vcc, 0, v0
	s_and_saveexec_b64 s[50:51], vcc
	s_cbranch_execz .LBB0_1131
	s_bcnt1_i32_b64 s34, s[52:53]
	v_mov_b32_e32 v1, s34
	global_atomic_add v193, v181, v1, s[48:49] sc0
.LBB0_1131:
	s_or_b64 exec, exec, s[50:51]
.LBB0_1132:
	s_or_b64 exec, exec, s[4:5]
	s_add_i32 s34, s56, 0x80
	s_add_i32 s56, s56, 0xffffffc0
	s_cmp_lt_i32 s56, 0
	s_cselect_b32 s56, s34, s56
	s_cmpk_lt_i32 s56, 0x80
	s_cbranch_scc0 .Lp4_perm_mla
	s_and_b32 s34, s56, 4
	s_lshl_b32 s34, s34, 4
	s_lshr_b32 s35, s56, 3
	s_lshl_b32 s35, s35, 2
	s_and_b32 s56, s56, 3
	s_or_b32 s56, s56, s34
	s_or_b32 s56, s56, s35
	s_branch .Lp4_perm_done

; __device__ __forceinline__ float bf2f(u16 h) { return __uint_as_float(((unsigned)h) << 16); }
; __device__ __forceinline__ u16 f2bf(float f) { return (u16)(cvtpk(f, 0.f) & 0xffffu); }
; template <int DK, bool KBIAS, int ROPE>
; __device__ __forceinline__ void attn_pp(const AttnArgs& a) {
;     ...
;   for (int d0 = 0; d0 < ND; ++d0) qr[d0] = *(const bf16x8*)(a.Q + (size_t)qpos * a.ldq + d0 * 16 + hi * 8);
;   if constexpr (ROPE == 1) {
; #pragma unroll
;     for (int dd = 0; dd < 2; ++dd)
; #pragma unroll
;       for (int e = 0; e < 8; ++e) {
;         float c, s; rope_cs(qpos, dd * 16 + hi * 8 + e, 64, c, s);
;         const float x1 = bf2f((u16)qr[8 + dd][e]), x2 = bf2f((u16)qr[10 + dd][e]);
;         qr[8 + dd][e] = (short)f2bf(x1 * c - x2 * s); qr[10 + dd][e] = (short)f2bf(x2 * c + x1 * s);
;       }
;   }
;   if constexpr (ROPE == 2) {
; #pragma unroll
;     for (int e = 0; e < 8; ++e) {
;       float c, s; rope_cs(qpos, hi * 8 + e, 32, c, s);
;       const float x1 = bf2f((u16)qr[0][e]), x2 = bf2f((u16)qr[1][e]);
;       qr[0][e] = (short)f2bf(x1 * c - x2 * s); qr[1][e] = (short)f2bf(x2 * c + x1 * s);
;     }
;   }
;   const int gt = tid & 255;
;   const int sr = grp * 32 + (gt >> 4), sc = (gt & 15) * 8;
;   const int sr2 = grp * 32 + (gt >> 3), sc2 = (gt & 7) * 8;
;   const int vst0 = v_st(sr, sc);
;   bf16x8 sk0, sk1, sk2, sv0, sv1; float sb = 0.f;
;   bf16x8 tk0, tk1, tk2, tv0, tv1; float tb = 0.f;
; __global__ void __launch_bounds__(NTHREADS) fwd_megakernel(Params p) {
;     ...
;     for (;;) {
;       __syncthreads();
;       if (tid == 0) s_item = pend;
;       __syncthreads();
;       const int n = s_item;
;       if (n >= 64) break;
;       if (tid == 0) pend = (int)atomicAdd(&ctr[8 + xq], 1u);
;       const int head32 = xq * 4 + (n >> 4), b = head32 >> 4, h = head32 & 15;
;       const size_t t0 = (size_t)b * SEQ;
;       AttnArgs a;
;       a.qb = 15 - (n & 15); a.kb = kbias + (size_t)(b * 16 + h) * SEQ;
;       a.Q = proj + t0 * NOP + O_FQ + h * 128; a.ldq = NOP;
;       a.K1 = proj + t0 * NOP + O_FK + h * 128; a.ldk1 = NOP;
;       a.K2 = nullptr; a.ldk2 = 0;
;       a.V = proj + t0 * NOP + O_FV + h * 128; a.ldv = NOP;
;       a.O = mixed + t0 * 4096 + 2048 + h * 128; a.ldo = 4096;
;       a.G = proj + t0 * NOP + O_GD + h * 128; a.ldg = NOP;
;       a.c2 = 0.08838834764831845f * LOG2E;
.LBB0_2052:
	s_barrier
	s_waitcnt vmcnt(63)
	s_and_saveexec_b64 s[4:5], s[0:1]
	ds_write_b32 v161, v172
	s_or_b64 exec, exec, s[4:5]
	s_waitcnt lgkmcnt(0)
	s_barrier
	ds_read_b32 v0, v161
	s_waitcnt lgkmcnt(0)
	v_cmp_lt_i32_e64 s[4:5], 63, v0
	v_readfirstlane_b32 s20, v0
	s_and_b64 vcc, exec, s[4:5]
	s_cbranch_vccnz .LBB0_2051
	s_and_saveexec_b64 s[6:7], s[0:1]
	s_cbranch_execz .LBB0_2059
	s_mov_b64 s[14:15], exec
	v_mbcnt_lo_u32_b32 v0, s14, 0
	v_mbcnt_hi_u32_b32 v0, s15, v0
	v_cmp_eq_u32_e32 vcc, 0, v0
	s_and_saveexec_b64 s[8:9], vcc
	s_cbranch_execz .LBB0_2058
	s_bcnt1_i32_b64 s14, s[14:15]
	v_mov_b32_e32 v1, s14
	global_atomic_add v172, v161, v1, s[12:13] offset:32 sc0
.LBB0_2058:
	s_or_b64 exec, exec, s[8:9]
.LBB0_2059:
	s_or_b64 exec, exec, s[6:7]
	s_lshl_b32 s48, s20, 4
	s_and_b32 s48, s48, 0x30
	s_lshr_b32 s20, s20, 2
	s_or_b32 s20, s20, s48
	s_ashr_i32 s48, s20, 4
	s_add_i32 s6, s48, s31
	s_ashr_i32 s7, s6, 31
	s_ashr_i32 s14, s6, 4
	s_lshl_b64 s[8:9], s[6:7], 14
	s_add_u32 s16, s22, s8
	s_addc_u32 s17, s23, s9
	s_mul_i32 s50, s14, 0x6c00000
	s_mul_hi_i32 s49, s14, 0x6c00000
	s_add_u32 s34, s42, s50
	s_addc_u32 s35, s43, s49
	s_lshl_b32 s6, s6, 7
	s_and_b32 s6, s6, 0x780
	s_lshl_b32 s36, s6, 1
	s_add_u32 s6, s34, s36
	s_addc_u32 s7, s35, 0
	s_add_u32 s8, s6, 0x2aa0
	s_addc_u32 s9, s7, 0
	s_add_u32 s18, s6, 0x3aa0
	s_addc_u32 s19, s7, 0
	s_add_u32 s6, s6, 0x4aa0
	v_mov_b32_e32 v162, v194
	s_addc_u32 s7, s7, 0
	s_not_b32 s15, s20
	v_readfirstlane_b32 s38, v162
	s_ashr_i32 s37, s38, 1
	s_lshl_b32 s15, s15, 8
	s_andn2_b32 s37, s37, 31
	s_and_b32 s39, s15, 0xf00
	v_and_b32_e32 v173, 31, v162
	s_add_i32 s33, s37, s39
	v_bfe_u32 v32, v162, 5, 1
	v_or_b32_e32 v174, s33, v173
	v_mov_b64_e32 v[0:1], s[8:9]
	v_mad_i64_i32 v[0:1], s[8:9], v174, s26, v[0:1]
	v_lshlrev_b32_e32 v164, 4, v32
	v_mov_b32_e32 v165, v161
	s_ashr_i32 s15, s38, 8
	v_lshl_add_u64 v[0:1], v[0:1], 0, v[164:165]
	s_lshl_b32 s51, s15, 5
	v_bfe_u32 v33, v162, 4, 4
	global_load_dwordx4 v[96:99], v[0:1], off
	global_load_dwordx4 v[100:103], v[0:1], off offset:32
	global_load_dwordx4 v[104:107], v[0:1], off offset:64
	global_load_dwordx4 v[108:111], v[0:1], off offset:96
	global_load_dwordx4 v[112:115], v[0:1], off offset:128
	global_load_dwordx4 v[116:119], v[0:1], off offset:160
	global_load_dwordx4 v[120:123], v[0:1], off offset:192
	global_load_dwordx4 v[124:127], v[0:1], off offset:224
	v_or_b32_e32 v35, s51, v33
	v_lshlrev_b32_e32 v0, 3, v162
	v_and_b32_e32 v36, 0x78, v0
	v_mov_b64_e32 v[0:1], s[18:19]
	v_or_b32_e32 v4, 16, v35
	v_mad_i64_i32 v[2:3], s[8:9], v35, s26, v[0:1]
	v_lshlrev_b32_e32 v160, 1, v36
	v_mad_i64_i32 v[0:1], s[8:9], v4, s26, v[0:1]
	v_lshl_add_u64 v[2:3], v[2:3], 0, v[160:161]
	v_lshl_add_u64 v[0:1], v[0:1], 0, v[160:161]
	s_barrier
	global_load_dwordx4 v[16:19], v[2:3], off
	global_load_dwordx4 v[20:23], v[0:1], off
	v_mov_b64_e32 v[0:1], s[6:7]
	v_mad_i64_i32 v[2:3], s[8:9], v35, s26, v[0:1]
	v_lshl_add_u64 v[2:3], v[2:3], 0, v[160:161]
	v_mad_i64_i32 v[0:1], s[8:9], v4, s26, v[0:1]
	v_lshl_add_u64 v[0:1], v[0:1], 0, v[160:161]
	global_load_dwordx4 v[24:27], v[2:3], off
	global_load_dwordx4 v[28:31], v[0:1], off
	v_cmp_gt_i32_e64 s[8:9], 64, v162
	v_mov_b32_e32 v34, 0
	v_ashrrev_i32_e32 v163, 31, v162
	v_mov_b32_e32 v175, 0
	s_and_saveexec_b64 s[20:21], s[8:9]
	s_cbranch_execz .LBB0_2061
	v_lshl_add_u64 v[0:1], v[162:163], 2, s[16:17]
	global_load_dword v175, v[0:1], off

; __device__ __forceinline__ float bf2f(u16 h) { return __uint_as_float(((unsigned)h) << 16); }
; __device__ __forceinline__ int otid() { int t = threadIdx.x; asm volatile("" : "+v"(t)); return t; }
; __device__ __forceinline__ void dsa_item(const Params& p, int tk0) {
;     ...
;   const int tid = otid(), wid = __builtin_amdgcn_readfirstlane(tid >> 6), lane = tid & 63, fr = lane & 15, fq = lane >> 4;
;   const int tk = tk0 + wid;
;   const int b = tk0 >> 12, qpos = tk & (SEQ - 1);
;   char* wl = g_lds + wid * DSA_WREG;
;   u16* selL = (u16*)wl;
;   char* Vw = wl + 1024;
;   char* kib = g_lds + DSA_KI_OFF;
;   bf16x8 qf[2];
; #pragma unroll
;   for (int ks = 0; ks < 2; ++ks) qf[ks] = *(const bf16x8*)(proj + (size_t)tk * NOP + O_IQ + fr * 64 + ks * 32 + fq * 8);
;   float w[4];
; #pragma unroll
;   for (int r = 0; r < 4; ++r) w[r] = bf2f(proj[(size_t)tk * NOP + O_IW + 4 * fq + r]) * (1.f / 32.f);
;   const int nblk = ((tk0 & (SEQ - 1)) >> 6) + 1;
;   const u16* kisrc = ki + (size_t)(b * SEQ + (tid >> 3)) * 64 + (tid & 7) * 8;
;   char* kidst = kib + (tid >> 3) * 160 + (tid & 7) * 16;
;   const char* kird = kib + fr * 160 + fq * 16;
;   const int nstep = (nblk + 1) >> 1;
;   bf16x8 st0 = *(const bf16x8*)kisrc, st1 = *(const bf16x8*)(kisrc + 64 * 64);
;   __syncthreads();
;   *(bf16x8*)kidst = st0; *(bf16x8*)(kidst + DSA_KI_BUF) = st1;
;   __syncthreads();
; __global__ void __launch_bounds__(NTHREADS) fwd_megakernel(Params p) {
;     ...
;     __syncthreads();
;     if (tid == 0) s_item = pend_d;
;     __syncthreads();
;     const int it = s_item;
;     if (it >= T_TOK / 8) break;
;     if (tid == 0) pend_d = (int)atomicAdd(&ctr[16], 1u);
;     const int b = it & 1, grp = 511 - (it >> 1);
;     ...
;     dsa_item(p, b * SEQ + grp * 8);
.LBB0_2228:
	s_barrier
	s_waitcnt vmcnt(63)
	s_and_saveexec_b64 s[2:3], s[0:1]
	ds_write_b32 v117, v120
	s_or_b64 exec, exec, s[2:3]
	s_waitcnt lgkmcnt(0)
	s_barrier
	ds_read_b32 v0, v117
	s_movk_i32 s2, 0x3ff
	s_waitcnt lgkmcnt(0)
	v_cmp_lt_i32_e64 s[2:3], s2, v0
	v_readfirstlane_b32 s8, v0
	s_nop 0
	v_writelane_b32 v241, s2, 0
	s_and_b64 vcc, exec, s[2:3]
	s_nop 0
	v_writelane_b32 v241, s3, 1
	s_cbranch_vccnz .LBB0_2227
	s_and_saveexec_b64 s[2:3], s[0:1]
	s_cbranch_execz .LBB0_2235
	s_mov_b64 s[6:7], exec
	v_mbcnt_lo_u32_b32 v0, s6, 0
	v_mbcnt_hi_u32_b32 v0, s7, v0
	v_cmp_eq_u32_e32 vcc, 0, v0
	s_and_saveexec_b64 s[4:5], vcc
	s_cbranch_execz .LBB0_2234
	s_bcnt1_i32_b64 s6, s[6:7]
	v_mov_b32_e32 v1, s6
	v_readlane_b32 s6, v241, 57
	v_readlane_b32 s7, v241, 58
	s_nop 4
	global_atomic_add v120, v117, v1, s[6:7] sc0
.LBB0_2234:
	s_or_b64 exec, exec, s[4:5]
.LBB0_2235:
	s_or_b64 exec, exec, s[2:3]
	s_lshl_b32 s2, s8, 12
	s_lshl_b32 s3, s8, 2
	s_and_b32 s2, s2, 0x1000
	s_and_b32 s3, s3, -8
	s_sub_i32 s2, s2, s3
	v_mov_b32_e32 v124, v194
	s_add_i32 s4, s2, 0xff8
	s_and_b32 s33, s4, 0x7ffff000
	v_readfirstlane_b32 s2, v124
	s_ashr_i32 s10, s2, 6
	s_add_i32 s6, s10, s4
	s_mul_i32 s3, s6, 0x6c00
	v_and_b32_e32 v123, 15, v124
	s_mul_hi_i32 s2, s6, 0x6c00
	s_mov_b32 s8, s6
	s_add_u32 s6, s42, s3
	s_addc_u32 s7, s43, s2
	v_lshlrev_b32_e32 v116, 7, v123
	v_lshl_add_u64 v[0:1], s[6:7], 0, v[116:117]
	v_and_b32_e32 v16, 48, v124
	v_mov_b32_e32 v17, v117
	v_lshl_add_u64 v[0:1], v[0:1], 0, v[16:17]
	s_mov_b64 s[2:3], 0x1200
	v_writelane_b32 v241, s6, 48
	v_ashrrev_i32_e32 v17, 3, v124
	v_lshl_add_u64 v[4:5], v[0:1], 0, s[2:3]
	v_add_co_u32_e32 v22, vcc, s9, v0
	v_writelane_b32 v241, s7, 49
	v_add_u32_e32 v0, s33, v17
	v_addc_co_u32_e32 v23, vcc, 0, v1, vcc
	v_ashrrev_i32_e32 v1, 31, v0
	v_readlane_b32 s2, v241, 42
	v_lshlrev_b64 v[0:1], 7, v[0:1]
	v_readlane_b32 s3, v241, 43
	v_lshlrev_b32_e32 v127, 4, v124
	v_and_b32_e32 v24, 0x70, v127
	v_lshl_add_u64 v[0:1], s[2:3], 0, v[0:1]
	v_mov_b32_e32 v25, v117
	v_bfe_u32 v125, v124, 4, 2
	v_lshl_add_u64 v[20:21], v[0:1], 0, v[24:25]
	s_movk_i32 s2, 0x2000
	v_lshlrev_b32_e32 v116, 3, v125
	global_load_dwordx4 v[0:3], v[4:5], off offset:64
	global_load_dwordx4 v[8:11], v[20:21], off
	v_add_co_u32_e32 v4, vcc, s2, v20
	v_lshl_add_u64 v[6:7], s[6:7], 0, v[116:117]
	s_nop 0
	v_addc_co_u32_e32 v5, vcc, 0, v21, vcc
	v_add_co_u32_e32 v26, vcc, s9, v6
	global_load_dwordx4 v[12:15], v[4:5], off
	s_nop 0
	v_addc_co_u32_e32 v27, vcc, 0, v7, vcc
	global_load_dwordx4 v[4:7], v[22:23], off offset:512
	global_load_dwordx2 v[18:19], v[26:27], off offset:2688
	s_movk_i32 s2, 0xa0
	v_mul_lo_u32 v17, v17, s2
	v_readlane_b32 s2, v241, 52
	s_bfe_u32 s11, s4, 0x60006
	s_nop 0
	v_add_u32_e32 v17, s2, v17
	s_add_i32 s2, s11, 2
	s_lshr_b32 s13, s2, 1
	s_add_i32 s13, s13, -1
	s_cmp_lg_u32 s13, 0
	s_cselect_b64 s[2:3], -1, 0
	v_add_u32_e32 v61, v17, v24
	s_and_b64 vcc, exec, s[2:3]
	s_barrier
	s_waitcnt vmcnt(3)
	ds_write_b128 v61, v[8:11]
	s_waitcnt vmcnt(2)
	ds_write_b128 v61, v[12:15] offset:10240
	s_waitcnt lgkmcnt(0)
	s_barrier
	s_cbranch_vccz .LBB0_2237
	v_add_co_u32_e32 v22, vcc, 0x4000, v20
	s_nop 1
	v_addc_co_u32_e32 v23, vcc, 0, v21, vcc
	v_add_co_u32_e32 v24, vcc, 0x6000, v20
	s_nop 1
	v_addc_co_u32_e32 v25, vcc, 0, v21, vcc
	global_load_dwordx4 v[8:11], v[22:23], off
	global_load_dwordx4 v[12:15], v[24:25], off
